# attention tile barrier moved in front of the last two PV MFMAs, next tile's first K fragments prefetched behind it; plus q/k epilogue load hoisting
# speedup vs baseline: 1.0131x; 1.0029x over previous
; __device__ __forceinline__ void attn_phase(int wv, const bf16_t* Q, const bf16_t* Kf, const bf16_t* Vt, const bf16_t* proj, bf16_t* mixed, LAS unsigned char* lds) { LIDS
;     ...
;             for (int t = 0; t < nt; ++t) {
;                 const int b = t & 1;
;                 asm volatile("s_waitcnt vmcnt(0)" ::: "memory"); __builtin_amdgcn_s_barrier(); asm volatile("" ::: "memory");
;                 if (t + 1 < nt) ATT_ISSUE(t + 1, b ^ 1);
.Lp2_loop0:
	s_waitcnt vmcnt(0)
	s_barrier
	s_add_i32 s22, s19, 2
	s_add_i32 s24, s19, 1
	s_cmp_gt_i32 s19, s21
	s_cbranch_scc1 .Lp2_idle0
	s_cmp_eq_u32 s19, s21
	s_cbranch_scc1 .Lp2_drain0
	ds_read_b128 v[160:163], v207 offset:0xa010
	ds_read_b128 v[164:167], v207 offset:0xd010
	ds_read_b128 v[168:171], v208 offset:0xa010
	ds_read_b128 v[172:175], v208 offset:0xd010
.Lp2_top0:
	s_waitcnt lgkmcnt(3)
	v_mfma_f32_32x32x16_bf16 v[228:243], v[160:163], v[112:115], v[0:15]
	ds_read_b128 v[160:163], v209 offset:0xa010
	v_exp_f32_e32 v96, v96
	v_exp_f32_e32 v97, v97
	s_nop 0
	v_add_f32_e32 v246, v96, v97
	s_waitcnt lgkmcnt(3)
	v_mfma_f32_32x32x16_bf16 v[178:193], v[164:167], v[112:115], v[0:15]
	ds_read_b128 v[164:167], v209 offset:0xd010
	v_cvt_pk_bf16_f32 v96, v96, v97
	v_exp_f32_e32 v98, v98
	v_exp_f32_e32 v99, v99
	s_cmp_ge_i32 s22, s17
	s_cbranch_scc1 .Lp2_nd3
	s_mov_b32 m0, s58
	s_nop 0
	global_load_lds_dwordx4 v176, s[62:63]

; __device__ __forceinline__ unsigned cvt_pk_bf16(float lo, float hi) { unsigned r; asm volatile("v_cvt_pk_bf16_f32 %0, %1, %2" : "=v"(r) : "v"(lo), "v"(hi)); return r; }
; #define LGK(n, f) asm volatile("s_waitcnt lgkmcnt(%1)" : "+v"(f) : "n"(n))
; #define ATT_VRD(j) DSR(fr_[(j) & 3], vad[(j) >> 2], ((j) & 3) * 4096)
; __device__ __forceinline__ void attn_phase(int wv, const bf16_t* Q, const bf16_t* Kf, const bf16_t* Vt, const bf16_t* proj, bf16_t* mixed, LAS unsigned char* lds) { LIDS
;     ...
;                     for (int c = 0; c < 4; ++c) {
;                         const int kb = c >> 1, sx = c & 1;
;                         u32x4 pw;
; #pragma unroll
;                         for (int j = 0; j < 4; ++j) pw[j] = cvt_pk_bf16(s[kb][8 * sx + 2 * j], s[kb][8 * sx + 2 * j + 1]);
;                         const bf16x8 pf = __builtin_bit_cast(bf16x8, pw);
; #pragma unroll
;                         for (int bb = 0; bb < 4; ++bb) {
;                             const int j = c * 4 + bb;
;                             LGK(j < 13 ? 3 : 15 - j, fr_[j & 3]);
;                             o[bb] = __builtin_amdgcn_mfma_f32_32x32x16_bf16(fr_[j & 3], pf, o[bb], 0, 0, 0);
;                             if (j + 4 < 16) ATT_VRD(j + 4);
;                         }
;                     }
.Lp2_nomask2:
	s_waitcnt lgkmcnt(3)
	v_mfma_f32_32x32x16_bf16 v[48:63], v[160:163], v[100:103], v[48:63]
	ds_read_b128 v[160:163], v220 offset:0x6010
	v_max3_f32 v226, v228, v229, v230
	v_max3_f32 v226, v226, v231, v232
	v_max3_f32 v226, v226, v233, v234
	v_max3_f32 v226, v226, v235, v236
	v_max3_f32 v226, v226, v237, v238
	s_waitcnt lgkmcnt(3)
	v_mfma_f32_32x32x16_bf16 v[32:47], v[164:167], v[100:103], v[32:47]
	ds_read_b128 v[164:167], v220 offset:0x7010
	v_max3_f32 v226, v226, v239, v240
	v_max3_f32 v226, v226, v241, v242
	v_max_f32_e32 v226, v226, v243
	v_max3_f32 v227, v178, v179, v180
	v_max3_f32 v227, v227, v181, v182
	s_waitcnt lgkmcnt(3)
	v_mfma_f32_32x32x16_bf16 v[16:31], v[168:171], v[100:103], v[16:31]
	ds_read_b128 v[168:171], v220 offset:0x8010
	v_max3_f32 v227, v227, v183, v184
	v_max3_f32 v227, v227, v185, v186
	v_max3_f32 v227, v227, v187, v188
	v_max3_f32 v227, v227, v189, v190
	v_max3_f32 v227, v227, v191, v192
	s_waitcnt lgkmcnt(3)
	v_mfma_f32_32x32x16_bf16 v[64:79], v[172:175], v[100:103], v[64:79]
	ds_read_b128 v[172:175], v220 offset:0x9010
	v_max_f32_e32 v227, v227, v193
	v_max_f32_e32 v226, v226, v227
	v_mov_b32_e32 v227, v226
	s_nop 1
	v_permlane32_swap_b32_e32 v226, v227
	v_max_f32_e32 v226, v226, v227
	s_waitcnt lgkmcnt(3)
	v_mfma_f32_32x32x16_bf16 v[48:63], v[160:163], v[80:83], v[48:63]
	ds_read_b128 v[160:163], v221 offset:0x6010
	s_waitcnt lgkmcnt(3)
	v_mfma_f32_32x32x16_bf16 v[32:47], v[164:167], v[80:83], v[32:47]
	ds_read_b128 v[164:167], v221 offset:0x7010
	s_waitcnt lgkmcnt(3)
	v_mfma_f32_32x32x16_bf16 v[16:31], v[168:171], v[80:83], v[16:31]
	ds_read_b128 v[168:171], v221 offset:0x8010
	s_waitcnt lgkmcnt(3)
	v_mfma_f32_32x32x16_bf16 v[64:79], v[172:175], v[80:83], v[64:79]
	ds_read_b128 v[172:175], v221 offset:0x9010
	s_waitcnt lgkmcnt(3)
	v_mfma_f32_32x32x16_bf16 v[48:63], v[160:163], v[84:87], v[48:63]
	s_waitcnt lgkmcnt(3)
	v_mfma_f32_32x32x16_bf16 v[32:47], v[164:167], v[84:87], v[32:47]
	s_waitcnt lgkmcnt(0)
	s_waitcnt vmcnt(0)
	s_barrier
	ds_read_b128 v[160:163], v207 offset:0x10
	ds_read_b128 v[164:167], v207 offset:0x3010
	s_waitcnt lgkmcnt(3)
	v_mfma_f32_32x32x16_bf16 v[16:31], v[168:171], v[84:87], v[16:31]
	ds_read_b128 v[168:171], v208 offset:0x10
	s_waitcnt lgkmcnt(3)
	v_mfma_f32_32x32x16_bf16 v[64:79], v[172:175], v[84:87], v[64:79]
	ds_read_b128 v[172:175], v208 offset:0x3010
	v_cmp_gt_f32_e32 vcc, v226, v247
	s_cbranch_vccnz .Lp2_rare0

; #define LAS __attribute__((address_space(3)))
; #define LGK(n, f) asm volatile("s_waitcnt lgkmcnt(%1)" : "+v"(f) : "n"(n))
; #define ATT_KRD(i) DSR(fr_[(i) & 3], kad[((i) >> 1) & 3], ((i) & 1) * (32 * 384) + ((i) >> 3) * 128)
; __device__ __forceinline__ void attn_phase(int wv, const bf16_t* Q, const bf16_t* Kf, const bf16_t* Vt, const bf16_t* proj, bf16_t* mixed, LAS unsigned char* lds) { LIDS
;     ...
;             for (int t = 0; t < nt; ++t) {
;                 const int b = t & 1;
;                 asm volatile("s_waitcnt vmcnt(0)" ::: "memory"); __builtin_amdgcn_s_barrier(); asm volatile("" ::: "memory");
;                 if (t + 1 < nt) ATT_ISSUE(t + 1, b ^ 1);
;                 if (64 * t <= qw0 + 31) {
;                     LAS unsigned char* kb_ = lds + b * ATT_STAGE; LAS unsigned char* vb_ = kb_ + ATT_KB;
;                     f32x16 s[2];
; #pragma unroll
;                     for (int kb = 0; kb < 2; ++kb)
; #pragma unroll
;                         for (int j = 0; j < 16; ++j) s[kb][j] = zf;
;                     unsigned kad[4];
; #pragma unroll
;                     for (int kl = 0; kl < 4; ++kl) kad[kl] = (unsigned)(size_t)kb_ + (unsigned)koffl[kl];
;                     bf16x8 fr_[4];
;     ...
;                     ATT_KRD(0); ATT_KRD(1); ATT_KRD(2); ATT_KRD(3);
; #pragma unroll
;                     for (int i = 0; i < 24; ++i) {
;                         LGK(i < 21 ? 3 : 23 - i, fr_[i & 3]);
;                         s[i & 1] = __builtin_amdgcn_mfma_f32_32x32x16_bf16(fr_[i & 3], qf[i >> 1], s[i & 1], 0, 0, 0);
;                         if (i + 4 < 24) ATT_KRD(i + 4);
;                     }
.Lp2_top1:
	s_waitcnt lgkmcnt(3)
	v_mfma_f32_32x32x16_bf16 v[96:111], v[160:163], v[112:115], v[0:15]
	ds_read_b128 v[160:163], v209 offset:0x10
	v_exp_f32_e32 v228, v228
	v_exp_f32_e32 v229, v229
	s_nop 0
	v_add_f32_e32 v246, v228, v229
	s_waitcnt lgkmcnt(3)
	v_mfma_f32_32x32x16_bf16 v[80:95], v[164:167], v[112:115], v[0:15]
	ds_read_b128 v[164:167], v209 offset:0x3010
	v_cvt_pk_bf16_f32 v228, v228, v229
	v_exp_f32_e32 v230, v230
	v_exp_f32_e32 v231, v231
	s_cmp_ge_i32 s22, s17
	s_cbranch_scc1 .Lp2_nd9
	s_add_i32 m0, s58, 0xa000
	s_nop 0
	global_load_lds_dwordx4 v176, s[62:63]

; __device__ __forceinline__ unsigned cvt_pk_bf16(float lo, float hi) { unsigned r; asm volatile("v_cvt_pk_bf16_f32 %0, %1, %2" : "=v"(r) : "v"(lo), "v"(hi)); return r; }
; #define LGK(n, f) asm volatile("s_waitcnt lgkmcnt(%1)" : "+v"(f) : "n"(n))
; #define ATT_VRD(j) DSR(fr_[(j) & 3], vad[(j) >> 2], ((j) & 3) * 4096)
; __device__ __forceinline__ void attn_phase(int wv, const bf16_t* Q, const bf16_t* Kf, const bf16_t* Vt, const bf16_t* proj, bf16_t* mixed, LAS unsigned char* lds) { LIDS
;     ...
;                     for (int c = 0; c < 4; ++c) {
;                         const int kb = c >> 1, sx = c & 1;
;                         u32x4 pw;
; #pragma unroll
;                         for (int j = 0; j < 4; ++j) pw[j] = cvt_pk_bf16(s[kb][8 * sx + 2 * j], s[kb][8 * sx + 2 * j + 1]);
;                         const bf16x8 pf = __builtin_bit_cast(bf16x8, pw);
; #pragma unroll
;                         for (int bb = 0; bb < 4; ++bb) {
;                             const int j = c * 4 + bb;
;                             LGK(j < 13 ? 3 : 15 - j, fr_[j & 3]);
;                             o[bb] = __builtin_amdgcn_mfma_f32_32x32x16_bf16(fr_[j & 3], pf, o[bb], 0, 0, 0);
;                             if (j + 4 < 16) ATT_VRD(j + 4);
;                         }
;                     }
.Lp2_nomask8:
	s_waitcnt lgkmcnt(3)
	v_mfma_f32_32x32x16_bf16 v[48:63], v[160:163], v[232:235], v[48:63]
	ds_read_b128 v[160:163], v212 offset:0x8010
	v_max3_f32 v226, v96, v97, v98
	v_max3_f32 v226, v226, v99, v100
	v_max3_f32 v226, v226, v101, v102
	v_max3_f32 v226, v226, v103, v104
	v_max3_f32 v226, v226, v105, v106
	s_waitcnt lgkmcnt(3)
	v_mfma_f32_32x32x16_bf16 v[32:47], v[164:167], v[232:235], v[32:47]
	ds_read_b128 v[164:167], v212 offset:0x9010
	v_max3_f32 v226, v226, v107, v108
	v_max3_f32 v226, v226, v109, v110
	v_max_f32_e32 v226, v226, v111
	v_max3_f32 v227, v80, v81, v82
	v_max3_f32 v227, v227, v83, v84
	s_waitcnt lgkmcnt(3)
	v_mfma_f32_32x32x16_bf16 v[16:31], v[168:171], v[232:235], v[16:31]
	ds_read_b128 v[168:171], v212 offset:0xa010
	v_max3_f32 v227, v227, v85, v86
	v_max3_f32 v227, v227, v87, v88
	v_max3_f32 v227, v227, v89, v90
	v_max3_f32 v227, v227, v91, v92
	v_max3_f32 v227, v227, v93, v94
	s_waitcnt lgkmcnt(3)
	v_mfma_f32_32x32x16_bf16 v[64:79], v[172:175], v[232:235], v[64:79]
	ds_read_b128 v[172:175], v212 offset:0xb010
	v_max_f32_e32 v227, v227, v95
	v_max_f32_e32 v226, v226, v227
	v_mov_b32_e32 v227, v226
	s_nop 1
	v_permlane32_swap_b32_e32 v226, v227
	v_max_f32_e32 v226, v226, v227
	s_waitcnt lgkmcnt(3)
	v_mfma_f32_32x32x16_bf16 v[48:63], v[160:163], v[178:181], v[48:63]
	ds_read_b128 v[160:163], v213 offset:0x8010
	s_waitcnt lgkmcnt(3)
	v_mfma_f32_32x32x16_bf16 v[32:47], v[164:167], v[178:181], v[32:47]
	ds_read_b128 v[164:167], v213 offset:0x9010
	s_waitcnt lgkmcnt(3)
	v_mfma_f32_32x32x16_bf16 v[16:31], v[168:171], v[178:181], v[16:31]
	ds_read_b128 v[168:171], v213 offset:0xa010
	s_waitcnt lgkmcnt(3)
	v_mfma_f32_32x32x16_bf16 v[64:79], v[172:175], v[178:181], v[64:79]
	ds_read_b128 v[172:175], v213 offset:0xb010
	s_waitcnt lgkmcnt(3)
	v_mfma_f32_32x32x16_bf16 v[48:63], v[160:163], v[182:185], v[48:63]
	s_waitcnt lgkmcnt(3)
	v_mfma_f32_32x32x16_bf16 v[32:47], v[164:167], v[182:185], v[32:47]
	s_waitcnt lgkmcnt(0)
	s_waitcnt vmcnt(0)
	s_barrier
	ds_read_b128 v[160:163], v207 offset:0xa010
	ds_read_b128 v[164:167], v207 offset:0xd010
	s_waitcnt lgkmcnt(3)
	v_mfma_f32_32x32x16_bf16 v[16:31], v[168:171], v[182:185], v[16:31]
	ds_read_b128 v[168:171], v208 offset:0xa010
	s_waitcnt lgkmcnt(3)
	v_mfma_f32_32x32x16_bf16 v[64:79], v[172:175], v[182:185], v[64:79]
	ds_read_b128 v[172:175], v208 offset:0xd010
	v_cmp_gt_f32_e32 vcc, v226, v247
	s_cbranch_vccnz .Lp2_rare1

; __device__ __forceinline__ void attn_phase(int wv, const bf16_t* Q, const bf16_t* Kf, const bf16_t* Vt, const bf16_t* proj, bf16_t* mixed, LAS unsigned char* lds) { LIDS
;     ...
;                 }
;             }
;             const float ltot = lsum + __shfl_xor(lsum, 32), inv = 1.0f / ltot;
.Lp2_exit:
	s_waitcnt lgkmcnt(0)
	s_nop 7
	s_branch .LBB0_96

; __device__ __forceinline__ void attn_phase(int wv, const bf16_t* Q, const bf16_t* Kf, const bf16_t* Vt, const bf16_t* proj, bf16_t* mixed, LAS unsigned char* lds) { LIDS
;     ...
;                 asm volatile("s_waitcnt vmcnt(0)" ::: "memory"); __builtin_amdgcn_s_barrier(); asm volatile("" ::: "memory");
.Lp2_nd18:
	s_waitcnt vmcnt(0)
	s_barrier
	s_branch .Lp2_tail0

; __device__ __forceinline__ unsigned cvt_pk_bf16(float lo, float hi) { unsigned r; asm volatile("v_cvt_pk_bf16_f32 %0, %1, %2" : "=v"(r) : "v"(lo), "v"(hi)); return r; }
; __device__ __forceinline__ float fast_exp2(float x) { return __builtin_amdgcn_exp2f(x); }
; #define LGK(n, f) asm volatile("s_waitcnt lgkmcnt(%1)" : "+v"(f) : "n"(n))
; #define ATT_VRD(j) DSR(fr_[(j) & 3], vad[(j) >> 2], ((j) & 3) * 4096)
; __device__ __forceinline__ void attn_phase(int wv, const bf16_t* Q, const bf16_t* Kf, const bf16_t* Vt, const bf16_t* proj, bf16_t* mixed, LAS unsigned char* lds) { LIDS
;     ...
;                     float ps = 0.f;
; #pragma unroll
;                     for (int kb = 0; kb < 2; ++kb)
; #pragma unroll
;                         for (int j = 0; j < 16; ++j) { s[kb][j] = fast_exp2(s[kb][j] - mrun); ps += s[kb][j]; }
;                     lsum += ps;
; #pragma unroll
;                     for (int c = 0; c < 4; ++c) {
;                         const int kb = c >> 1, sx = c & 1;
;                         u32x4 pw;
; #pragma unroll
;                         for (int j = 0; j < 4; ++j) pw[j] = cvt_pk_bf16(s[kb][8 * sx + 2 * j], s[kb][8 * sx + 2 * j + 1]);
;                         const bf16x8 pf = __builtin_bit_cast(bf16x8, pw);
; #pragma unroll
;                         for (int bb = 0; bb < 4; ++bb) {
;                             const int j = c * 4 + bb;
;                             LGK(j < 13 ? 3 : 15 - j, fr_[j & 3]);
;                             o[bb] = __builtin_amdgcn_mfma_f32_32x32x16_bf16(fr_[j & 3], pf, o[bb], 0, 0, 0);
;                             if (j + 4 < 16) ATT_VRD(j + 4);
;                         }
;                     }
.Lp2_nd28:
	v_exp_f32_e32 v96, v96
	v_exp_f32_e32 v97, v97
	s_nop 0
	v_add_f32_e32 v246, v96, v97
	v_cvt_pk_bf16_f32 v96, v96, v97
	v_exp_f32_e32 v98, v98
	v_exp_f32_e32 v99, v99
	v_add_f32_e32 v246, v246, v98
	v_add_f32_e32 v246, v246, v99
	v_cvt_pk_bf16_f32 v97, v98, v99
	v_exp_f32_e32 v100, v100
	v_exp_f32_e32 v101, v101
	v_add_f32_e32 v246, v246, v100
	v_add_f32_e32 v246, v246, v101
	v_cvt_pk_bf16_f32 v98, v100, v101
	v_exp_f32_e32 v102, v102
	v_exp_f32_e32 v103, v103
	v_add_f32_e32 v246, v246, v102
	v_add_f32_e32 v246, v246, v103
	v_cvt_pk_bf16_f32 v99, v102, v103
	s_waitcnt lgkmcnt(3)
	s_nop 0
	v_mfma_f32_32x32x16_bf16 v[48:63], v[160:163], v[96:99], v[48:63]
	ds_read_b128 v[160:163], v219 offset:0x6010
	v_exp_f32_e32 v104, v104
	v_exp_f32_e32 v105, v105
	v_add_f32_e32 v246, v246, v104
	v_add_f32_e32 v246, v246, v105
	v_cvt_pk_bf16_f32 v100, v104, v105
	s_waitcnt lgkmcnt(3)
	v_mfma_f32_32x32x16_bf16 v[32:47], v[164:167], v[96:99], v[32:47]
	ds_read_b128 v[164:167], v219 offset:0x7010
	v_exp_f32_e32 v106, v106
	v_exp_f32_e32 v107, v107
	v_add_f32_e32 v246, v246, v106
	v_add_f32_e32 v246, v246, v107
	v_cvt_pk_bf16_f32 v101, v106, v107
	s_waitcnt lgkmcnt(3)
	v_mfma_f32_32x32x16_bf16 v[16:31], v[168:171], v[96:99], v[16:31]
	ds_read_b128 v[168:171], v219 offset:0x8010
	v_exp_f32_e32 v108, v108
	v_exp_f32_e32 v109, v109
	v_add_f32_e32 v246, v246, v108
	v_add_f32_e32 v246, v246, v109
	v_cvt_pk_bf16_f32 v102, v108, v109
	s_waitcnt lgkmcnt(3)
	v_mfma_f32_32x32x16_bf16 v[64:79], v[172:175], v[96:99], v[64:79]
	ds_read_b128 v[172:175], v219 offset:0x9010
	v_exp_f32_e32 v110, v110
	v_exp_f32_e32 v111, v111
	v_add_f32_e32 v246, v246, v110
	v_add_f32_e32 v246, v246, v111
	v_cvt_pk_bf16_f32 v103, v110, v111
	s_waitcnt lgkmcnt(3)
	s_nop 0
	v_mfma_f32_32x32x16_bf16 v[48:63], v[160:163], v[100:103], v[48:63]
	ds_read_b128 v[160:163], v220 offset:0x6010
	v_exp_f32_e32 v80, v80
	v_exp_f32_e32 v81, v81
	v_add_f32_e32 v246, v246, v80
	v_add_f32_e32 v246, v246, v81
	v_cvt_pk_bf16_f32 v80, v80, v81
	s_waitcnt lgkmcnt(3)
	v_mfma_f32_32x32x16_bf16 v[32:47], v[164:167], v[100:103], v[32:47]
	ds_read_b128 v[164:167], v220 offset:0x7010
	v_exp_f32_e32 v82, v82
	v_exp_f32_e32 v83, v83
	v_add_f32_e32 v246, v246, v82
	v_add_f32_e32 v246, v246, v83
	v_cvt_pk_bf16_f32 v81, v82, v83
	s_waitcnt lgkmcnt(3)
	v_mfma_f32_32x32x16_bf16 v[16:31], v[168:171], v[100:103], v[16:31]
	ds_read_b128 v[168:171], v220 offset:0x8010
	v_exp_f32_e32 v84, v84
	v_exp_f32_e32 v85, v85
	v_add_f32_e32 v246, v246, v84
	v_add_f32_e32 v246, v246, v85
	v_cvt_pk_bf16_f32 v82, v84, v85
	s_waitcnt lgkmcnt(3)
	v_mfma_f32_32x32x16_bf16 v[64:79], v[172:175], v[100:103], v[64:79]
	ds_read_b128 v[172:175], v220 offset:0x9010
	v_exp_f32_e32 v86, v86
	v_exp_f32_e32 v87, v87
	v_add_f32_e32 v246, v246, v86
	v_add_f32_e32 v246, v246, v87
	v_cvt_pk_bf16_f32 v83, v86, v87
	s_waitcnt lgkmcnt(3)
	s_nop 0
	v_mfma_f32_32x32x16_bf16 v[48:63], v[160:163], v[80:83], v[48:63]
	ds_read_b128 v[160:163], v221 offset:0x6010
	v_exp_f32_e32 v88, v88
	v_exp_f32_e32 v89, v89
	v_add_f32_e32 v246, v246, v88
	v_add_f32_e32 v246, v246, v89
	v_cvt_pk_bf16_f32 v84, v88, v89
	s_waitcnt lgkmcnt(3)
	v_mfma_f32_32x32x16_bf16 v[32:47], v[164:167], v[80:83], v[32:47]
	ds_read_b128 v[164:167], v221 offset:0x7010
	v_exp_f32_e32 v90, v90
	v_exp_f32_e32 v91, v91
	v_add_f32_e32 v246, v246, v90
	v_add_f32_e32 v246, v246, v91
	v_cvt_pk_bf16_f32 v85, v90, v91
	s_waitcnt lgkmcnt(3)
	v_mfma_f32_32x32x16_bf16 v[16:31], v[168:171], v[80:83], v[16:31]
	ds_read_b128 v[168:171], v221 offset:0x8010
	v_exp_f32_e32 v92, v92
	v_exp_f32_e32 v93, v93
	v_add_f32_e32 v246, v246, v92
	v_add_f32_e32 v246, v246, v93
	v_cvt_pk_bf16_f32 v86, v92, v93
	s_waitcnt lgkmcnt(3)
	v_mfma_f32_32x32x16_bf16 v[64:79], v[172:175], v[80:83], v[64:79]
	ds_read_b128 v[172:175], v221 offset:0x9010
	v_exp_f32_e32 v94, v94
	v_exp_f32_e32 v95, v95
	v_add_f32_e32 v246, v246, v94
	v_add_f32_e32 v246, v246, v95
	v_cvt_pk_bf16_f32 v87, v94, v95
	s_waitcnt lgkmcnt(3)
	s_nop 0
	v_mfma_f32_32x32x16_bf16 v[48:63], v[160:163], v[84:87], v[48:63]
	v_add_f32_e32 v224, v224, v246
	s_waitcnt lgkmcnt(2)
	v_mfma_f32_32x32x16_bf16 v[32:47], v[164:167], v[84:87], v[32:47]
	s_waitcnt lgkmcnt(1)
	v_mfma_f32_32x32x16_bf16 v[16:31], v[168:171], v[84:87], v[16:31]
	s_waitcnt lgkmcnt(0)
	v_mfma_f32_32x32x16_bf16 v[64:79], v[172:175], v[84:87], v[64:79]
	s_waitcnt lgkmcnt(0)
	s_waitcnt vmcnt(0)
	s_barrier
	s_branch .Lp2_tail0

; __device__ __forceinline__ unsigned cvt_pk_bf16(float lo, float hi) { unsigned r; asm volatile("v_cvt_pk_bf16_f32 %0, %1, %2" : "=v"(r) : "v"(lo), "v"(hi)); return r; }
; __device__ __forceinline__ float fast_exp2(float x) { return __builtin_amdgcn_exp2f(x); }
; #define LGK(n, f) asm volatile("s_waitcnt lgkmcnt(%1)" : "+v"(f) : "n"(n))
; #define ATT_VRD(j) DSR(fr_[(j) & 3], vad[(j) >> 2], ((j) & 3) * 4096)
; __device__ __forceinline__ void attn_phase(int wv, const bf16_t* Q, const bf16_t* Kf, const bf16_t* Vt, const bf16_t* proj, bf16_t* mixed, LAS unsigned char* lds) { LIDS
;     ...
;                     float ps = 0.f;
; #pragma unroll
;                     for (int kb = 0; kb < 2; ++kb)
; #pragma unroll
;                         for (int j = 0; j < 16; ++j) { s[kb][j] = fast_exp2(s[kb][j] - mrun); ps += s[kb][j]; }
;                     lsum += ps;
; #pragma unroll
;                     for (int c = 0; c < 4; ++c) {
;                         const int kb = c >> 1, sx = c & 1;
;                         u32x4 pw;
; #pragma unroll
;                         for (int j = 0; j < 4; ++j) pw[j] = cvt_pk_bf16(s[kb][8 * sx + 2 * j], s[kb][8 * sx + 2 * j + 1]);
;                         const bf16x8 pf = __builtin_bit_cast(bf16x8, pw);
; #pragma unroll
;                         for (int bb = 0; bb < 4; ++bb) {
;                             const int j = c * 4 + bb;
;                             LGK(j < 13 ? 3 : 15 - j, fr_[j & 3]);
;                             o[bb] = __builtin_amdgcn_mfma_f32_32x32x16_bf16(fr_[j & 3], pf, o[bb], 0, 0, 0);
;                             if (j + 4 < 16) ATT_VRD(j + 4);
;                         }
;                     }
.Lp2_nd33:
	v_exp_f32_e32 v228, v228
	v_exp_f32_e32 v229, v229
	s_nop 0
	v_add_f32_e32 v246, v228, v229
	v_cvt_pk_bf16_f32 v228, v228, v229
	v_exp_f32_e32 v230, v230
	v_exp_f32_e32 v231, v231
	v_add_f32_e32 v246, v246, v230
	v_add_f32_e32 v246, v246, v231
	v_cvt_pk_bf16_f32 v229, v230, v231
	v_exp_f32_e32 v232, v232
	v_exp_f32_e32 v233, v233
	v_add_f32_e32 v246, v246, v232
	v_add_f32_e32 v246, v246, v233
	v_cvt_pk_bf16_f32 v230, v232, v233
	v_exp_f32_e32 v234, v234
	v_exp_f32_e32 v235, v235
	v_add_f32_e32 v246, v246, v234
	v_add_f32_e32 v246, v246, v235
	v_cvt_pk_bf16_f32 v231, v234, v235
	s_waitcnt lgkmcnt(3)
	s_nop 0
	v_mfma_f32_32x32x16_bf16 v[48:63], v[160:163], v[228:231], v[48:63]
	ds_read_b128 v[160:163], v211 offset:0x8010
	v_exp_f32_e32 v236, v236
	v_exp_f32_e32 v237, v237
	v_add_f32_e32 v246, v246, v236
	v_add_f32_e32 v246, v246, v237
	v_cvt_pk_bf16_f32 v232, v236, v237
	s_waitcnt lgkmcnt(3)
	v_mfma_f32_32x32x16_bf16 v[32:47], v[164:167], v[228:231], v[32:47]
	ds_read_b128 v[164:167], v211 offset:0x9010
	v_exp_f32_e32 v238, v238
	v_exp_f32_e32 v239, v239
	v_add_f32_e32 v246, v246, v238
	v_add_f32_e32 v246, v246, v239
	v_cvt_pk_bf16_f32 v233, v238, v239
	s_waitcnt lgkmcnt(3)
	v_mfma_f32_32x32x16_bf16 v[16:31], v[168:171], v[228:231], v[16:31]
	ds_read_b128 v[168:171], v211 offset:0xa010
	v_exp_f32_e32 v240, v240
	v_exp_f32_e32 v241, v241
	v_add_f32_e32 v246, v246, v240
	v_add_f32_e32 v246, v246, v241
	v_cvt_pk_bf16_f32 v234, v240, v241
	s_waitcnt lgkmcnt(3)
	v_mfma_f32_32x32x16_bf16 v[64:79], v[172:175], v[228:231], v[64:79]
	ds_read_b128 v[172:175], v211 offset:0xb010
	v_exp_f32_e32 v242, v242
	v_exp_f32_e32 v243, v243
	v_add_f32_e32 v246, v246, v242
	v_add_f32_e32 v246, v246, v243
	v_cvt_pk_bf16_f32 v235, v242, v243
	s_waitcnt lgkmcnt(3)
	s_nop 0
	v_mfma_f32_32x32x16_bf16 v[48:63], v[160:163], v[232:235], v[48:63]
	ds_read_b128 v[160:163], v212 offset:0x8010
	v_exp_f32_e32 v178, v178
	v_exp_f32_e32 v179, v179
	v_add_f32_e32 v246, v246, v178
	v_add_f32_e32 v246, v246, v179
	v_cvt_pk_bf16_f32 v178, v178, v179
	s_waitcnt lgkmcnt(3)
	v_mfma_f32_32x32x16_bf16 v[32:47], v[164:167], v[232:235], v[32:47]
	ds_read_b128 v[164:167], v212 offset:0x9010
	v_exp_f32_e32 v180, v180
	v_exp_f32_e32 v181, v181
	v_add_f32_e32 v246, v246, v180
	v_add_f32_e32 v246, v246, v181
	v_cvt_pk_bf16_f32 v179, v180, v181
	s_waitcnt lgkmcnt(3)
	v_mfma_f32_32x32x16_bf16 v[16:31], v[168:171], v[232:235], v[16:31]
	ds_read_b128 v[168:171], v212 offset:0xa010
	v_exp_f32_e32 v182, v182
	v_exp_f32_e32 v183, v183
	v_add_f32_e32 v246, v246, v182
	v_add_f32_e32 v246, v246, v183
	v_cvt_pk_bf16_f32 v180, v182, v183
	s_waitcnt lgkmcnt(3)
	v_mfma_f32_32x32x16_bf16 v[64:79], v[172:175], v[232:235], v[64:79]
	ds_read_b128 v[172:175], v212 offset:0xb010
	v_exp_f32_e32 v184, v184
	v_exp_f32_e32 v185, v185
	v_add_f32_e32 v246, v246, v184
	v_add_f32_e32 v246, v246, v185
	v_cvt_pk_bf16_f32 v181, v184, v185
	s_waitcnt lgkmcnt(3)
	s_nop 0
	v_mfma_f32_32x32x16_bf16 v[48:63], v[160:163], v[178:181], v[48:63]
	ds_read_b128 v[160:163], v213 offset:0x8010
	v_exp_f32_e32 v186, v186
	v_exp_f32_e32 v187, v187
	v_add_f32_e32 v246, v246, v186
	v_add_f32_e32 v246, v246, v187
	v_cvt_pk_bf16_f32 v182, v186, v187
	s_waitcnt lgkmcnt(3)
	v_mfma_f32_32x32x16_bf16 v[32:47], v[164:167], v[178:181], v[32:47]
	ds_read_b128 v[164:167], v213 offset:0x9010
	v_exp_f32_e32 v188, v188
	v_exp_f32_e32 v189, v189
	v_add_f32_e32 v246, v246, v188
	v_add_f32_e32 v246, v246, v189
	v_cvt_pk_bf16_f32 v183, v188, v189
	s_waitcnt lgkmcnt(3)
	v_mfma_f32_32x32x16_bf16 v[16:31], v[168:171], v[178:181], v[16:31]
	ds_read_b128 v[168:171], v213 offset:0xa010
	v_exp_f32_e32 v190, v190
	v_exp_f32_e32 v191, v191
	v_add_f32_e32 v246, v246, v190
	v_add_f32_e32 v246, v246, v191
	v_cvt_pk_bf16_f32 v184, v190, v191
	s_waitcnt lgkmcnt(3)
	v_mfma_f32_32x32x16_bf16 v[64:79], v[172:175], v[178:181], v[64:79]
	ds_read_b128 v[172:175], v213 offset:0xb010
	v_exp_f32_e32 v192, v192
	v_exp_f32_e32 v193, v193
	v_add_f32_e32 v246, v246, v192
	v_add_f32_e32 v246, v246, v193
	v_cvt_pk_bf16_f32 v185, v192, v193
	s_waitcnt lgkmcnt(3)
	s_nop 0
	v_mfma_f32_32x32x16_bf16 v[48:63], v[160:163], v[182:185], v[48:63]
	v_add_f32_e32 v224, v224, v246
	s_waitcnt lgkmcnt(2)
	v_mfma_f32_32x32x16_bf16 v[32:47], v[164:167], v[182:185], v[32:47]
	s_waitcnt lgkmcnt(1)
	v_mfma_f32_32x32x16_bf16 v[16:31], v[168:171], v[182:185], v[16:31]
	s_waitcnt lgkmcnt(0)
	v_mfma_f32_32x32x16_bf16 v[64:79], v[172:175], v[182:185], v[64:79]
	s_waitcnt lgkmcnt(0)
	s_waitcnt vmcnt(0)
	s_barrier
	s_branch .Lp2_tail1
